# MLA lazy rescale: row reference set 2.0 (log2) above the tile row max on a rescale
# speedup vs baseline: 1.0118x; 1.0036x over previous
; __device__ __forceinline__ void partialSM9(f32x16& p0, f32x16& p1, float& m_run, float& alpha, const float thr2) {
;   float pmax = p0[0];
; #pragma unroll
;   for (int r = 1; r < 16; ++r) pmax = fmaxf(pmax, p0[r]);
; #pragma unroll
;   for (int r = 0; r < 16; ++r) pmax = fmaxf(pmax, p1[r]);
;   { auto rr = __builtin_amdgcn_permlane32_swap(__float_as_uint(pmax), __float_as_uint(pmax), false, false);
;     pmax = fmaxf(__uint_as_float(rr[0]), __uint_as_float(rr[1])); }
;   if (__builtin_expect(__all(pmax <= 7.0f + thr2), 1)) { alpha = 1.f; }
;   else { const float delta = fmaxf(pmax - 7.0f, 0.f); alpha = __builtin_amdgcn_exp2f(-delta); m_run += delta;
; #pragma unroll
;     for (int r = 0; r < 16; ++r) { p0[r] -= delta; p1[r] -= delta; } }
; }
.Lmla_h0_newmax:
	v_add_f32_e32 v0, 0xc0a00000, v177
	v_max_f32_e32 v177, 0, v0
	v_exp_f32_e64 v221, -v177
	v_add_f32_e32 v217, v217, v177
	v_sub_f32_e32 v129, v129, v177
	v_sub_f32_e32 v128, v128, v177
	v_sub_f32_e32 v127, v127, v177
	v_sub_f32_e32 v126, v126, v177
	v_sub_f32_e32 v125, v125, v177
	v_sub_f32_e32 v124, v124, v177
	v_sub_f32_e32 v123, v123, v177
	v_sub_f32_e32 v122, v122, v177
	v_sub_f32_e32 v121, v121, v177
	v_sub_f32_e32 v120, v120, v177
	v_sub_f32_e32 v119, v119, v177
	v_sub_f32_e32 v118, v118, v177
	v_sub_f32_e32 v117, v117, v177
	v_sub_f32_e32 v116, v116, v177
	v_sub_f32_e32 v115, v115, v177
	v_sub_f32_e32 v114, v114, v177
	s_and_saveexec_b64 s[20:21], s[40:41]
	ds_write_b32 v208, v221 offset:41088
	s_or_b64 exec, exec, s[20:21]
	v_sub_f32_e32 v113, v113, v177
	v_sub_f32_e32 v112, v112, v177
	v_sub_f32_e32 v111, v111, v177
	v_sub_f32_e32 v110, v110, v177
	v_sub_f32_e32 v109, v109, v177
	v_sub_f32_e32 v108, v108, v177
	v_sub_f32_e32 v107, v107, v177
	v_sub_f32_e32 v106, v106, v177
	v_sub_f32_e32 v105, v105, v177
	v_sub_f32_e32 v104, v104, v177
	v_sub_f32_e32 v103, v103, v177
	v_sub_f32_e32 v102, v102, v177
	v_sub_f32_e32 v101, v101, v177
	v_sub_f32_e32 v100, v100, v177
	v_sub_f32_e32 v99, v99, v177
	v_sub_f32_e32 v98, v98, v177
	v_sub_f32_e32 v230, 0x40e00000, v217
	v_mov_b32_e32 v231, v230
	v_mov_b32_e32 v232, v230
	v_mov_b32_e32 v233, v230
	v_mov_b32_e32 v234, v230
	v_mov_b32_e32 v235, v230
	v_mov_b32_e32 v236, v230
	v_mov_b32_e32 v237, v230
	v_mov_b32_e32 v238, v230
	v_mov_b32_e32 v239, v230
	v_mov_b32_e32 v240, v230
	v_mov_b32_e32 v241, v230
	v_mov_b32_e32 v242, v230
	v_mov_b32_e32 v243, v230
	v_mov_b32_e32 v244, v230
	v_mov_b32_e32 v245, v230
	v_add_u32_e32 v0, v187, v207
	s_waitcnt lgkmcnt(0)
	ds_read_b128 v[66:69], v0 offset:41184
	ds_read_b128 v[70:73], v0 offset:41152
	ds_read_b128 v[74:77], v0 offset:41120
	ds_read_b128 v[78:81], v0 offset:41088
	s_waitcnt lgkmcnt(0)
	v_pk_mul_f32 v[62:63], v[62:63], v[66:67]
	v_pk_mul_f32 v[58:59], v[58:59], v[70:71]
	v_pk_mul_f32 v[54:55], v[54:55], v[74:75]
	v_pk_mul_f32 v[64:65], v[64:65], v[68:69]
	v_pk_mul_f32 v[60:61], v[60:61], v[72:73]
	v_pk_mul_f32 v[56:57], v[56:57], v[76:77]
	v_pk_mul_f32 v[52:53], v[52:53], v[80:81]
	v_pk_mul_f32 v[50:51], v[50:51], v[78:79]
	v_pk_mul_f32 v[46:47], v[46:47], v[66:67]
	v_pk_mul_f32 v[42:43], v[42:43], v[70:71]
	v_pk_mul_f32 v[38:39], v[38:39], v[74:75]
	v_pk_mul_f32 v[48:49], v[48:49], v[68:69]
	v_pk_mul_f32 v[44:45], v[44:45], v[72:73]
	v_pk_mul_f32 v[40:41], v[40:41], v[76:77]
	v_pk_mul_f32 v[36:37], v[36:37], v[80:81]
	v_pk_mul_f32 v[34:35], v[34:35], v[78:79]
	v_pk_mul_f32 v[30:31], v[30:31], v[66:67]
	v_pk_mul_f32 v[26:27], v[26:27], v[70:71]
	v_pk_mul_f32 v[22:23], v[22:23], v[74:75]
	v_pk_mul_f32 v[32:33], v[32:33], v[68:69]
	v_pk_mul_f32 v[28:29], v[28:29], v[72:73]
	v_pk_mul_f32 v[24:25], v[24:25], v[76:77]
	v_pk_mul_f32 v[20:21], v[20:21], v[80:81]
	v_pk_mul_f32 v[18:19], v[18:19], v[78:79]
	v_pk_mul_f32 v[14:15], v[14:15], v[66:67]
	v_pk_mul_f32 v[10:11], v[10:11], v[70:71]
	v_pk_mul_f32 v[6:7], v[6:7], v[74:75]
	v_pk_mul_f32 v[16:17], v[16:17], v[68:69]
	v_pk_mul_f32 v[12:13], v[12:13], v[72:73]
	v_pk_mul_f32 v[8:9], v[8:9], v[76:77]
	v_pk_mul_f32 v[4:5], v[4:5], v[80:81]
	v_pk_mul_f32 v[2:3], v[2:3], v[78:79]
	s_branch .Lmla_h0_cont
.Lmla_h1_newmax:
	v_add_f32_e32 v0, 0xc0a00000, v177
	v_max_f32_e32 v177, 0, v0
	v_exp_f32_e64 v218, -v177
	v_add_f32_e32 v217, v217, v177
	v_sub_f32_e32 v97, v97, v177
	v_sub_f32_e32 v96, v96, v177
	v_sub_f32_e32 v95, v95, v177
	v_sub_f32_e32 v94, v94, v177
	v_sub_f32_e32 v93, v93, v177
	v_sub_f32_e32 v92, v92, v177
	v_sub_f32_e32 v91, v91, v177
	v_sub_f32_e32 v90, v90, v177
	v_sub_f32_e32 v89, v89, v177
	v_sub_f32_e32 v88, v88, v177
	v_sub_f32_e32 v87, v87, v177
	v_sub_f32_e32 v86, v86, v177
	v_sub_f32_e32 v85, v85, v177
	v_sub_f32_e32 v84, v84, v177
	v_sub_f32_e32 v83, v83, v177
	v_sub_f32_e32 v82, v82, v177
	s_and_saveexec_b64 s[20:21], s[40:41]
	ds_write_b32 v208, v218 offset:41088
	s_or_b64 exec, exec, s[20:21]
	v_sub_f32_e32 v81, v81, v177
	v_sub_f32_e32 v80, v80, v177
	v_sub_f32_e32 v79, v79, v177
	v_sub_f32_e32 v78, v78, v177
	v_sub_f32_e32 v77, v77, v177
	v_sub_f32_e32 v76, v76, v177
	v_sub_f32_e32 v75, v75, v177
	v_sub_f32_e32 v74, v74, v177
	v_sub_f32_e32 v73, v73, v177
	v_sub_f32_e32 v72, v72, v177
	v_sub_f32_e32 v71, v71, v177
	v_sub_f32_e32 v70, v70, v177
	v_sub_f32_e32 v69, v69, v177
	v_sub_f32_e32 v68, v68, v177
	v_sub_f32_e32 v67, v67, v177
	v_sub_f32_e32 v66, v66, v177
	v_sub_f32_e32 v230, 0x40e00000, v217
	v_mov_b32_e32 v231, v230
	v_mov_b32_e32 v232, v230
	v_mov_b32_e32 v233, v230
	v_mov_b32_e32 v234, v230
	v_mov_b32_e32 v235, v230
	v_mov_b32_e32 v236, v230
	v_mov_b32_e32 v237, v230
	v_mov_b32_e32 v238, v230
	v_mov_b32_e32 v239, v230
	v_mov_b32_e32 v240, v230
	v_mov_b32_e32 v241, v230
	v_mov_b32_e32 v242, v230
	v_mov_b32_e32 v243, v230
	v_mov_b32_e32 v244, v230
	v_mov_b32_e32 v245, v230
	v_add_u32_e32 v0, v187, v207
	s_waitcnt lgkmcnt(0)
	ds_read_b128 v[98:101], v0 offset:41184
	ds_read_b128 v[102:105], v0 offset:41152
	ds_read_b128 v[106:109], v0 offset:41120
	ds_read_b128 v[110:113], v0 offset:41088
	s_waitcnt lgkmcnt(0)
	v_pk_mul_f32 v[62:63], v[62:63], v[98:99]
	v_pk_mul_f32 v[58:59], v[58:59], v[102:103]
	v_pk_mul_f32 v[54:55], v[54:55], v[106:107]
	v_pk_mul_f32 v[64:65], v[64:65], v[100:101]
	v_pk_mul_f32 v[60:61], v[60:61], v[104:105]
	v_pk_mul_f32 v[56:57], v[56:57], v[108:109]
	v_pk_mul_f32 v[52:53], v[52:53], v[112:113]
	v_pk_mul_f32 v[50:51], v[50:51], v[110:111]
	v_pk_mul_f32 v[46:47], v[46:47], v[98:99]
	v_pk_mul_f32 v[42:43], v[42:43], v[102:103]
	v_pk_mul_f32 v[38:39], v[38:39], v[106:107]
	v_pk_mul_f32 v[48:49], v[48:49], v[100:101]
	v_pk_mul_f32 v[44:45], v[44:45], v[104:105]
	v_pk_mul_f32 v[40:41], v[40:41], v[108:109]
	v_pk_mul_f32 v[36:37], v[36:37], v[112:113]
	v_pk_mul_f32 v[34:35], v[34:35], v[110:111]
	v_pk_mul_f32 v[30:31], v[30:31], v[98:99]
	v_pk_mul_f32 v[26:27], v[26:27], v[102:103]
	v_pk_mul_f32 v[22:23], v[22:23], v[106:107]
	v_pk_mul_f32 v[32:33], v[32:33], v[100:101]
	v_pk_mul_f32 v[28:29], v[28:29], v[104:105]
	v_pk_mul_f32 v[24:25], v[24:25], v[108:109]
	v_pk_mul_f32 v[20:21], v[20:21], v[112:113]
	v_pk_mul_f32 v[18:19], v[18:19], v[110:111]
	v_pk_mul_f32 v[14:15], v[14:15], v[98:99]
	v_pk_mul_f32 v[10:11], v[10:11], v[102:103]
	v_pk_mul_f32 v[6:7], v[6:7], v[106:107]
	v_pk_mul_f32 v[16:17], v[16:17], v[100:101]
	v_pk_mul_f32 v[12:13], v[12:13], v[104:105]
	v_pk_mul_f32 v[8:9], v[8:9], v[108:109]
	v_pk_mul_f32 v[4:5], v[4:5], v[112:113]
	v_pk_mul_f32 v[2:3], v[2:3], v[110:111]
	s_branch .Lmla_h1_cont

; #define SWRITE(b) do { *(bf16x8*)(V_lds + (b) * SHM_V + vst0) = vs0; *(bf16x8*)(V_lds + (b) * SHM_V + vst1) = vs1; const int kc = sc * 2;  \
;     *(bf16x8*)(K_lds + (b) * SHM_K + KSWZ(sr, kc)) = ks0; *(bf16x8*)(K_lds + (b) * SHM_K + KSWZ(32 + sr, kc)) = ks1; \
;     if constexpr (NR > 0) *(bf16x8*)(Kr_lds + (b) * SHM_KR + krst) = kr; } while (0)
; #define SWRITE(b) do { *(bf16x8*)(V_lds + (b) * SHM_V + vst0) = vs0; *(bf16x8*)(V_lds + (b) * SHM_V + vst0 + 8192) = vs1;  \
;     *(bf16x8*)(K_lds + (b) * SHM_K + kst0) = ks0; *(bf16x8*)(K_lds + (b) * SHM_K + kst0 + 8192) = ks1; \
;     if constexpr (NR > 0) *(bf16x8*)(Kr_lds + (b) * SHM_KR + krst) = kr; } while (0)
; #define SWRITE(b) do { *(bf16x8*)(V_lds + (b) * 16384 + vst0) = vs0; *(bf16x8*)(V_lds + (b) * 16384 + vst0 + 8192) = vs1;  \
;     *(v4i32*)(Kn_lds + (b) * 8192 + knst) = kn; if (krw) *(v4i32*)(Kr_lds + (b) * 4096 + krst) = kr; } while (0)
; #define SWRITE(b) do { *(v4i32*)(Vt_lds + (b) * 8192 + vtst) = vt; *(v4i32*)(Kn_lds + (b) * 8192 + knst) = kn; if (krw) *(v4i32*)(Kr_lds + (b) * 4096 + krst) = kr; } while (0)
; __device__ __forceinline__ void partialSM9(f32x16& p0, f32x16& p1, float& m_run, float& alpha, const float thr2) {
;     ...
;   if (__builtin_expect(__all(pmax <= 7.0f + thr2), 1)) { alpha = 1.f; }
;   else { const float delta = fmaxf(pmax - 7.0f, 0.f); alpha = __builtin_amdgcn_exp2f(-delta); m_run += delta;
; #pragma unroll
;     for (int r = 0; r < 16; ++r) { p0[r] -= delta; p1[r] -= delta; } }
; }
; __device__ __forceinline__ void attn_unit7(const unsigned char* __restrict__ Q8, int ldq, const unsigned char* __restrict__ Kn8, int ldk, const unsigned char* __restrict__ Kr8, ...
;     ...
;   qkt9(pA0, pA1, Kn_lds, Kr_lds, qf, 7.0f - m_reg, r32, hi); partialSM9(pA0, pA1, m_reg, alA, thr_raw);
;   SWRITE(1); __syncthreads();
.LBB0_1350:
	v_add_f32_e32 v0, 0xc0a00000, v0
	v_max_f32_e32 v217, 0, v0
	v_exp_f32_e64 v218, -v217
	v_sub_f32_e32 v97, v97, v217
	v_sub_f32_e32 v96, v96, v217
	v_sub_f32_e32 v95, v95, v217
	v_sub_f32_e32 v94, v94, v217
	v_sub_f32_e32 v93, v93, v217
	v_sub_f32_e32 v92, v92, v217
	v_sub_f32_e32 v91, v91, v217
	v_sub_f32_e32 v90, v90, v217
	v_sub_f32_e32 v89, v89, v217
	v_sub_f32_e32 v88, v88, v217
	v_sub_f32_e32 v87, v87, v217
	v_sub_f32_e32 v86, v86, v217
	v_sub_f32_e32 v85, v85, v217
	v_sub_f32_e32 v84, v84, v217
	v_sub_f32_e32 v83, v83, v217
	v_sub_f32_e32 v82, v82, v217
	v_sub_f32_e32 v81, v81, v217
	v_sub_f32_e32 v80, v80, v217
	v_sub_f32_e32 v79, v79, v217
	v_sub_f32_e32 v78, v78, v217
	v_sub_f32_e32 v77, v77, v217
	v_sub_f32_e32 v76, v76, v217
	v_sub_f32_e32 v75, v75, v217
	v_sub_f32_e32 v74, v74, v217
	v_sub_f32_e32 v73, v73, v217
	v_sub_f32_e32 v72, v72, v217
	v_sub_f32_e32 v71, v71, v217
	v_sub_f32_e32 v70, v70, v217
	v_sub_f32_e32 v69, v69, v217
	v_sub_f32_e32 v68, v68, v217
	v_sub_f32_e32 v67, v67, v217
	v_sub_f32_e32 v66, v66, v217
	s_waitcnt vmcnt(0)
	ds_write_b128 v210, v[2:5] offset:8192
	ds_write_b128 v211, v[6:9] offset:24576
	s_and_saveexec_b64 s[20:21], s[42:43]
	s_cbranch_execnz .LBB0_1319
	s_branch .LBB0_1320
